# adaLN GEMM output loop: loop-invariant bias load hoisted, per-iteration vmcnt(0) removed
# speedup vs baseline: 1.0109x; 1.0109x over previous
.LBB0_174:
	s_waitcnt lgkmcnt(0)
	s_barrier
	s_and_saveexec_b64 s[18:19], s[0:1]
	s_cbranch_execz .LBB0_159
	s_mul_hi_i32 s21, s20, 0x38e38e39
	s_lshr_b32 s25, s21, 31
	s_ashr_i32 s21, s21, 6
	s_add_i32 s21, s21, s25
	v_lshl_or_b32 v2, s20, 5, v116
	s_mul_i32 s20, s21, 0x88
	s_mulk_i32 s21, 0x2400
	v_add_u32_e32 v6, s20, v188
	s_sub_i32 s20, s22, s21
	s_ashr_i32 s21, s20, 31
	s_lshl_b64 s[20:21], s[20:21], 2
	v_readlane_b32 s36, v249, 1
	v_mov_b64_e32 v[4:5], s[20:21]
	s_mov_b32 s20, 0x9000
	v_ashrrev_i32_e32 v3, 31, v2
	v_readlane_b32 s44, v249, 9
	v_readlane_b32 s45, v249, 10
	v_mad_i64_i32 v[4:5], s[20:21], v6, s20, v[4:5]
	s_nop 0
	v_lshl_add_u64 v[2:3], v[2:3], 2, s[44:45]
	v_lshl_add_u64 v[4:5], v[186:187], 0, v[4:5]
	s_mov_b64 s[20:21], 0
	v_mov_b32_e32 v6, v189
	v_mov_b32_e32 v7, v202
	v_readlane_b32 s37, v249, 2
	v_readlane_b32 s38, v249, 3
	v_readlane_b32 s39, v249, 4
	v_readlane_b32 s40, v249, 5
	v_readlane_b32 s41, v249, 6
	v_readlane_b32 s42, v249, 7
	v_readlane_b32 s43, v249, 8
	v_readlane_b32 s46, v249, 11
	v_readlane_b32 s47, v249, 12
	v_readlane_b32 s48, v249, 13
	v_readlane_b32 s49, v249, 14
	v_readlane_b32 s50, v249, 15
	v_readlane_b32 s51, v249, 16
	global_load_dword v254, v[2:3], off
	s_waitcnt vmcnt(0)
.LBB0_176:
	ds_read_b32 v9, v6
	v_add_u32_e32 v7, 16, v7
	s_movk_i32 s25, 0x77
	v_cmp_lt_i32_e32 vcc, s25, v7
	s_mov_b64 s[26:27], 0x90000
	v_add_u32_e32 v6, 0x840, v6
	s_or_b64 s[20:21], vcc, s[20:21]
	s_waitcnt lgkmcnt(0)
	v_add_f32_e32 v8, v9, v254
	global_store_dword v[4:5], v8, off
	v_lshl_add_u64 v[4:5], v[4:5], 0, s[26:27]
	s_andn2_b64 exec, exec, s[20:21]
	s_cbranch_execnz .LBB0_176
	s_branch .LBB0_159
